# FFN-up -> down barrier replaced by per-panel counters when every workgroup verified XCC_ID == blockIdx&7 (same-L2 producers/consumers; full barrier otherwise)
# baseline (speedup 1.0000x reference)
_Z11mega_kernel6Paramsii:
	s_mov_b32 s101, 0
	s_load_dword s21, s[0:1], 0x138
	v_writelane_b32 v253, s2, 0
	s_add_u32 s2, s0, 0x138
	s_addc_u32 s3, s1, 0
	v_writelane_b32 v253, s2, 1
	v_and_b32_e32 v1, 0x3ff, v0
	s_nop 0
	v_writelane_b32 v253, s3, 2
	s_mov_b32 s2, 0
	s_ashr_i32 s3, s2, 31
	s_add_u32 s2, s0, s2
	v_writelane_b32 v253, s0, 3
	s_addc_u32 s3, s1, s3
	s_nop 0
	v_writelane_b32 v253, s1, 4
	s_load_dwordx2 s[0:1], s[2:3], 0xb8
	v_cmp_eq_u32_e64 s[2:3], 0, v1
	s_waitcnt lgkmcnt(0)
	v_writelane_b32 v253, s0, 5
	s_nop 1
	v_writelane_b32 v253, s1, 6
	s_getreg_b32 s0, hwreg(HW_REG_XCC_ID, 0, 4)
	s_and_b32 s4, s0, 15
	s_mov_b64 s[0:1], exec
	v_writelane_b32 v253, s2, 7
	s_nop 1
	v_writelane_b32 v253, s3, 8
	s_and_b64 s[2:3], s[0:1], s[2:3]
	s_mov_b64 exec, s[2:3]
	s_cbranch_execz .LBB0_3
	s_add_i32 s5, 0, 0x24000
	s_cmp_lg_u32 s5, -1
	s_mov_b64 s[6:7], src_shared_base
	s_cselect_b32 s5, s5, 0
	s_cselect_b32 s6, s7, 0
	v_mov_b32_e32 v2, s5
	s_add_i32 s5, 0, 0x24004
	s_cmp_lg_u32 s5, -1
	v_mov_b32_e32 v3, s6
	v_mov_b32_e32 v4, 0
	s_cselect_b32 s5, s5, 0
	s_cselect_b32 s6, s7, 0
	s_mov_b64 s[2:3], exec
	flat_store_dword v[2:3], v4 sc0 sc1
	s_waitcnt vmcnt(0)
	v_mov_b32_e32 v2, s5
	v_mov_b32_e32 v3, s6
	flat_store_dword v[2:3], v4 sc0 sc1
	s_waitcnt vmcnt(0)
	v_mbcnt_lo_u32_b32 v2, s2, 0
	v_mbcnt_hi_u32_b32 v2, s3, v2
	v_cmp_eq_u32_e32 vcc, 0, v2
	s_and_b64 s[6:7], exec, vcc
	s_mov_b64 exec, s[6:7]
	s_cbranch_execz .LBB0_3
	s_bcnt1_i32_b64 s2, s[2:3]
	s_lshl_b32 s5, s4, 8
	v_mov_b32_e32 v3, s2
	v_readlane_b32 s2, v253, 5
	v_mov_b32_e32 v2, s5
	v_readlane_b32 s3, v253, 6
	s_nop 4
	global_atomic_add v2, v3, s[2:3] offset:1024
	v_readlane_b32 s5, v253, 0
	s_and_b32 s5, s5, 7
	s_cmp_lg_u32 s5, s4
	s_cselect_b32 s5, 1, 0
	v_mov_b32_e32 v3, s5
	v_mov_b32_e32 v2, 0x180
	global_atomic_add v2, v3, s[2:3]
.LBB0_3:
	s_or_b64 exec, exec, s[0:1]
	v_writelane_b32 v252, 0, 40
	v_readlane_b32 s0, v253, 3
	v_readlane_b32 s1, v253, 4
	s_load_dwordx2 s[10:11], s[0:1], 0x130
	s_waitcnt lgkmcnt(0)
	s_cmp_ge_i32 s10, s11
	s_cbranch_scc1 .Ltr_LBB0_783
	s_ashr_i32 s0, s21, 31
	v_writelane_b32 v253, s0, 9
	s_lshl_b32 s30, s21, 3
	s_ashr_i32 s20, s21, 3
	s_lshl_b32 s38, s21, 4
	v_readlane_b32 s6, v253, 5
	v_readlane_b32 s7, v253, 6
	s_add_u32 s68, s6, 0x200
	s_addc_u32 s69, s7, 0
	s_add_u32 s42, s6, 0x1000
	s_addc_u32 s43, s7, 0
	s_add_u32 s44, s6, 0x1100
	s_addc_u32 s45, s7, 0
	s_add_u32 s52, s6, 0x1200
	s_addc_u32 s53, s7, 0
	s_add_u32 s54, s6, 0x1300
	s_addc_u32 s55, s7, 0
	s_cmp_eq_u32 s4, 15
	s_cselect_b64 s[0:1], -1, 0
	v_writelane_b32 v253, s0, 10
	s_cmp_eq_u32 s4, 14
	s_mov_b32 s8, s21
	v_writelane_b32 v253, s1, 11
	s_cselect_b64 s[0:1], -1, 0
	v_writelane_b32 v253, s0, 12
	s_cmp_eq_u32 s4, 13
	v_mov_b32_e32 v163, 0
	v_writelane_b32 v253, s1, 13
	s_cselect_b64 s[0:1], -1, 0
	v_writelane_b32 v253, s0, 14
	s_cmp_eq_u32 s4, 12
	v_mov_b32_e32 v164, 0x358637bd
	v_writelane_b32 v253, s1, 15
	s_cselect_b64 s[0:1], -1, 0
	v_writelane_b32 v253, s0, 16
	s_cmp_eq_u32 s4, 11
	v_mov_b32_e32 v165, 1
	v_writelane_b32 v253, s1, 17
	s_cselect_b64 s[0:1], -1, 0
	v_writelane_b32 v253, s0, 18
	s_cmp_eq_u32 s4, 10
	v_mov_b64_e32 v[168:169], 0x2bf
	v_writelane_b32 v253, s1, 19
	s_cselect_b64 s[0:1], -1, 0
	v_writelane_b32 v253, s0, 20
	s_cmp_eq_u32 s4, 9
	v_mov_b32_e32 v202, 0xc00
	v_writelane_b32 v253, s1, 21
	s_cselect_b64 s[0:1], -1, 0
	v_writelane_b32 v253, s0, 22
	s_cmp_eq_u32 s4, 8
	v_mov_b32_e32 v203, 0x7ffffc00
	v_writelane_b32 v253, s1, 23
	s_cselect_b64 s[0:1], -1, 0
	v_writelane_b32 v253, s0, 24
	s_cmp_eq_u32 s4, 7
	v_mov_b32_e32 v204, 0xffffff00
	v_writelane_b32 v253, s1, 25
	s_cselect_b64 s[0:1], -1, 0
	v_writelane_b32 v253, s0, 26
	s_cmp_eq_u32 s4, 6
	v_mov_b32_e32 v205, 0x400
	v_writelane_b32 v253, s1, 27
	s_cselect_b64 s[0:1], -1, 0
	v_writelane_b32 v253, s0, 28
	s_cmp_eq_u32 s4, 5
	v_mov_b32_e32 v206, 0x100
	v_writelane_b32 v253, s1, 29
	s_cselect_b64 s[0:1], -1, 0
	v_writelane_b32 v253, s0, 30
	s_cmp_eq_u32 s4, 4
	v_mov_b32_e32 v207, 0x3ff
	v_writelane_b32 v253, s1, 31
	s_cselect_b64 s[0:1], -1, 0
	v_writelane_b32 v253, s0, 32
	s_cmp_eq_u32 s4, 3
	v_mov_b32_e32 v208, 0xff
	v_writelane_b32 v253, s1, 33
	s_cselect_b64 s[0:1], -1, 0
	v_writelane_b32 v253, s0, 34
	s_cmp_eq_u32 s4, 2
	v_mov_b64_e32 v[170:171], 0x340
	v_writelane_b32 v253, s1, 35
	s_cselect_b64 s[0:1], -1, 0
	v_writelane_b32 v253, s0, 36
	s_cmp_eq_u32 s4, 1
	v_mov_b64_e32 v[172:173], 0x33f
	v_writelane_b32 v253, s1, 37
	s_cselect_b64 s[0:1], -1, 0
	v_writelane_b32 v253, s0, 38
	s_cmp_eq_u32 s4, 0
	v_mov_b32_e32 v209, 0xcf
	v_writelane_b32 v253, s1, 39
	s_cselect_b64 s[0:1], -1, 0
	v_writelane_b32 v253, s0, 40
	v_mov_b32_e32 v210, 0xdf
	v_mov_b32_e32 v211, 0xef
	v_writelane_b32 v253, s1, 41
	s_lshl_b32 s0, s4, 8
	s_add_u32 s0, s6, s0
	s_addc_u32 s1, s7, 0
	s_add_u32 s2, s0, 0x1400
	s_addc_u32 s3, s1, 0
	v_writelane_b32 v253, s2, 42
	s_add_u32 s0, s0, 0x2400
	s_addc_u32 s1, s1, 0
	v_writelane_b32 v253, s3, 43
	v_writelane_b32 v253, s0, 44
	s_movk_i32 s29, 0x6000
	s_movk_i32 s22, 0xc00
	v_writelane_b32 v253, s1, 45
	s_add_u32 s0, s6, 0x3400
	s_addc_u32 s1, s7, 0
	v_writelane_b32 v253, s0, 46
	s_movk_i32 s23, 0x3400
	s_mov_b32 s33, 0x3e000000
	v_writelane_b32 v253, s1, 47
	s_add_u32 s0, s6, 0x3500
	s_addc_u32 s1, s7, 0
	v_writelane_b32 v253, s0, 48
	s_mov_b32 s49, 0
	s_mov_b64 s[26:27], 0x80
	v_writelane_b32 v253, s1, 49
	s_abs_i32 s0, s21
	v_cvt_f32_u32_e32 v2, s0
	s_sub_i32 s1, 0, s0
	s_mov_b64 s[34:35], 0x2000
	v_rcp_iflag_f32_e32 v2, v2
	s_nop 0
	v_mul_f32_e32 v2, 0x4f7ffffe, v2
	v_cvt_u32_f32_e32 v2, v2
	s_nop 0
	v_readfirstlane_b32 s2, v2
	s_mul_i32 s1, s1, s2
	s_mul_hi_u32 s1, s2, s1
	s_add_i32 s2, s2, s1
	s_mul_hi_u32 s1, s2, 0x2c0
	s_mul_i32 s1, s1, s0
	s_sub_i32 s1, 0x2c0, s1
	s_sub_i32 s3, s1, s0
	s_cmp_ge_u32 s1, s0
	s_cselect_b32 s1, s3, s1
	s_sub_i32 s3, s1, s0
	s_cmp_ge_u32 s1, s0
	s_cselect_b32 s3, s3, s1
	s_cmp_eq_u32 s3, 0
	s_cselect_b64 s[4:5], -1, 0
	s_sub_i32 s1, s21, s3
	v_writelane_b32 v253, s1, 50
	s_mul_hi_u32 s1, s2, 0x340
	s_mul_i32 s1, s1, s0
	s_sub_i32 s1, 0x340, s1
	s_sub_i32 s2, s1, s0
	s_cmp_ge_u32 s1, s0
	s_cselect_b32 s1, s2, s1
	s_sub_i32 s2, s1, s0
	s_cmp_ge_u32 s1, s0
	s_cselect_b32 s0, s2, s1
	s_cmp_eq_u32 s0, 0
	s_cselect_b64 s[6:7], -1, 0
	v_writelane_b32 v253, s6, 51
	s_lshl_b32 s1, s21, 9
	s_ashr_i32 s31, s30, 31
	v_writelane_b32 v253, s7, 52
	v_writelane_b32 v253, s0, 53
	s_sub_i32 s0, s21, s0
	v_writelane_b32 v253, s0, 54
	s_lshl_b32 s0, s21, 1
	v_writelane_b32 v253, s0, 55
	s_lshl_b32 s0, s3, 9
	v_writelane_b32 v253, s3, 56
	s_sub_i32 s2, 0, s0
	v_writelane_b32 v253, s2, 57
	v_writelane_b32 v253, s1, 58
	s_sub_i32 s0, s1, s0
	v_writelane_b32 v253, s0, 59
	s_add_i32 s0, 0, 0x10400
	v_writelane_b32 v253, s0, 60
	s_add_i32 s0, 0, 0x18400
	v_writelane_b32 v253, s0, 61
	s_lshl_b64 s[0:1], s[30:31], 12
	v_writelane_b32 v253, s0, 62
	v_writelane_b32 v254, s4, 0
	s_lshl_b64 s[40:41], s[30:31], 11
	v_writelane_b32 v253, s1, 63
	v_writelane_b32 v254, s5, 1
	s_xor_b64 s[0:1], s[4:5], -1
	v_writelane_b32 v254, s0, 2
	s_ashr_i32 s39, s38, 31
	s_lshl_b64 s[56:57], s[38:39], 11
	v_writelane_b32 v254, s1, 3
	v_writelane_b32 v254, s8, 4
	v_writelane_b32 v254, s20, 5
	v_writelane_b32 v254, s30, 6
	s_add_i32 s28, 0, 0x14000
	v_mbcnt_lo_u32_b32 v2, -1, 0
	v_writelane_b32 v254, s31, 7
	v_writelane_b32 v254, s38, 8
	v_mbcnt_hi_u32_b32 v194, -1, v2
	v_and_b32_e32 v2, 64, v194
	v_writelane_b32 v254, s39, 9
	v_writelane_b32 v254, s68, 10
	v_add_u32_e32 v195, 64, v2
	v_xor_b32_e32 v196, 32, v194
	v_writelane_b32 v254, s69, 11
	v_writelane_b32 v254, s42, 12
	v_xor_b32_e32 v197, 16, v194
	v_xor_b32_e32 v198, 8, v194
	v_writelane_b32 v254, s43, 13
	v_writelane_b32 v254, s44, 14
	v_xor_b32_e32 v199, 4, v194
	v_xor_b32_e32 v200, 2, v194
	v_writelane_b32 v254, s45, 15
	v_writelane_b32 v254, s52, 16
	v_xor_b32_e32 v201, 1, v194
	s_nop 0
	v_writelane_b32 v254, s53, 17
	v_writelane_b32 v254, s54, 18
	s_nop 1
	v_writelane_b32 v254, s55, 19
	v_writelane_b32 v254, s40, 20
	s_nop 1
	v_writelane_b32 v254, s41, 21
	v_writelane_b32 v254, s56, 22
	s_nop 1
	v_writelane_b32 v254, s57, 23
	s_branch .LBB0_6

.LBB0_8:
	v_writelane_b32 v254, s78, 24
	s_mov_b32 s0, s49
	s_ashr_i32 s1, s0, 31
	v_writelane_b32 v254, s79, 25
	v_writelane_b32 v254, s76, 26
	v_readlane_b32 s2, v253, 3
	v_readlane_b32 s3, v253, 4
	v_writelane_b32 v254, s77, 27
	v_writelane_b32 v254, s74, 28
	s_add_u32 s0, s2, s0
	s_addc_u32 s1, s3, s1
	v_writelane_b32 v254, s75, 29
	v_writelane_b32 v254, s66, 30
	v_readlane_b32 s24, v253, 62
	v_writelane_b32 v254, s67, 31
	v_readlane_b32 s25, v253, 63
	s_load_dwordx16 s[52:67], s[0:1], 0x0
	s_load_dwordx2 s[30:31], s[0:1], 0x70
	s_load_dwordx4 s[36:39], s[0:1], 0x60
	s_load_dwordx8 s[12:19], s[0:1], 0x40
	s_load_dwordx2 s[2:3], s[0:1], 0x88
	s_load_dwordx8 s[68:75], s[0:1], 0x98
	s_load_dwordx16 s[80:95], s[0:1], 0xc0
	s_load_dwordx4 s[96:99], s[0:1], 0x120
	s_load_dwordx8 s[4:11], s[0:1], 0x100
	s_waitcnt lgkmcnt(0)
	s_cmp_eq_u32 s46, 1
	s_cbranch_scc0 .Lpf_nodec
	v_readlane_b32 s0, v253, 5
	v_readlane_b32 s1, v253, 6
	v_mov_b32_e32 v2, 0x180
	s_nop 3
	global_load_dword v2, v2, s[0:1] sc1
	s_waitcnt vmcnt(0)
	v_readfirstlane_b32 s0, v2
	s_cmp_eq_u32 s0, 0
	s_cselect_b32 s0, 1, 0
	v_writelane_b32 v252, s0, 40
.Lpf_nodec:
	s_movk_i32 s100, 0
	s_cmp_eq_u32 s46, 6
	s_cselect_b32 s100, 8, s100
	s_cmp_eq_u32 s46, 10
	s_cselect_b32 s100, 16, s100
	s_cmp_eq_u32 s46, 15
	s_cselect_b32 s100, 24, s100
	s_cmp_eq_u32 s46, 19
	s_cselect_b32 s100, 32, s100
	s_cmp_eq_u32 s100, 0
	s_cbranch_scc1 .Lpf_done
	v_lshrrev_b32_e32 v2, 6, v1
	s_nop 1
	v_readfirstlane_b32 s0, v2
	s_cmp_lg_u32 s0, 0
	s_cbranch_scc1 .Lpf_wait
	v_readlane_b32 s0, v253, 0
	s_lshr_b32 s1, s0, 4
	s_mov_b32 vcc_lo, 15
	s_mov_b32 vcc_hi, 0
	s_cmp_eq_u32 s46, 19
	s_cbranch_scc0 .Lpf_t1
	s_lshr_b32 s1, s0, 5
	s_mov_b32 vcc_lo, 7

.Ldn_tile:
	s_and_b32 s0, s78, 3
	s_or_b32 s0, s0, s77
	v_readlane_b32 s12, v252, 40
	s_cmp_eq_u32 s12, 0
	s_cbranch_scc1 .Ldn_uacqs
	s_cmp_lg_u32 s76, 0
	s_cbranch_scc1 .Ldn_uacqw
	v_readlane_b32 s12, v253, 5
	v_readlane_b32 s13, v253, 6
	s_and_b32 s2, s0, 0xfffffffc
	s_lshl_b32 s2, s2, 2
	s_add_u32 s2, s2, 0x280
	v_lshlrev_b32_e32 v170, 2, v194
	v_add_u32_e32 v170, s2, v170
	s_add_i32 s3, s82, 1
	s_lshl_b32 s3, s3, 3
	s_movk_i32 s14, 0x1000
	s_mov_b64 exec, 15
.Ldn_uacqp:
	global_load_dword v171, v170, s[12:13] sc1
	s_waitcnt vmcnt(0)
	v_cmp_gt_u32_e32 vcc, s3, v171
	s_cbranch_vccz .Ldn_uacqok
	s_sleep 1
	s_add_i32 s14, s14, -1
	s_cmp_lg_u32 s14, 0
	s_cbranch_scc1 .Ldn_uacqp
.Ldn_uacqok:
	s_mov_b64 exec, -1
	buffer_inv sc1
	s_waitcnt vmcnt(0)

.Ldn_uacqs:
	s_cmp_lt_u32 s0, 16
	s_cbranch_scc1 .Ldn_afdone
	s_and_b32 s12, s0, 3
	v_lshrrev_b32_e32 v142, 6, v1
	s_nop 0
	v_readfirstlane_b32 s13, v142
	v_lshlrev_b32_e32 v130, 2, v1
	v_add_u32_e32 v131, 0x800, v130
	v_add_u32_e32 v132, 0x1000, v130
	v_add_u32_e32 v133, 0x1800, v130
	v_add_u32_e32 v134, 0x2000, v130
	v_add_u32_e32 v135, 0x2800, v130
	v_lshlrev_b32_e32 v136, 1, v1
	v_add_u32_e32 v137, 0x400, v136
	v_add_u32_e32 v138, 0x800, v136
	v_add_u32_e32 v139, 0xc00, v136
	v_add_u32_e32 v140, 0x1000, v136
	v_add_u32_e32 v141, 0x1400, v136
	s_mul_i32 s2, s82, 0x8400
	s_add_u32 s16, s38, s2
	s_addc_u32 s17, s39, 0
	s_cmp_eq_u32 s12, 0
	s_cbranch_scc1 .Ldn_afl
	s_mul_i32 s2, s0, 0x5800
	s_add_u32 s14, s6, s2
	s_addc_u32 s15, s7, 0
	s_nop 0
	global_load_dword v66, v130, s[14:15]
	global_load_dword v70, v131, s[14:15]
	global_load_dword v74, v132, s[14:15]
	global_load_dword v78, v133, s[14:15]
	global_load_dword v82, v134, s[14:15]
	s_cmp_gt_u32 s13, 3
	s_cbranch_scc1 .Ldn_af66a
	global_load_dword v86, v135, s[14:15]

.LBB0_727:
	s_mov_b64 s[2:3], s[46:47]
	s_add_i32 s18, s2, 1
	s_cmp_ge_i32 s18, s3
	v_readlane_b32 s30, v254, 6
	v_readlane_b32 s38, v254, 8
	v_readlane_b32 s56, v254, 22
	v_readlane_b32 s31, v254, 7
	v_readlane_b32 s39, v254, 9
	v_readlane_b32 s57, v254, 23
	s_cbranch_scc1 .LBB0_781
	s_cmp_eq_u32 s2, 7
	s_cbranch_scc1 .Lpf_uprel
	s_cmp_eq_u32 s2, 16
	s_cbranch_scc0 .Lpf_nouprel
.Lpf_uprel:
	v_readlane_b32 s4, v252, 40
	s_cmp_eq_u32 s4, 0
	s_cbranch_scc1 .Lpf_nouprel
	s_waitcnt vmcnt(0)
	s_barrier
	v_lshrrev_b32_e32 v2, 6, v1
	s_nop 1
	v_readfirstlane_b32 s4, v2
	s_cmp_lg_u32 s4, 0
	s_cbranch_scc1 .LBB0_781
	v_readlane_b32 s4, v253, 5
	v_readlane_b32 s5, v253, 6
	v_readlane_b32 s6, v253, 0
	s_and_b32 s7, s6, 7
	s_lshl_b32 s7, s7, 2
	s_bfe_u32 s6, s6, 0x20003
	s_or_b32 s6, s6, s7
	s_lshl_b32 s6, s6, 2
	s_add_u32 s6, s6, 0x280
	v_mov_b32_e32 v2, s6
	v_mov_b32_e32 v3, 1
	s_nop 3
	s_mov_b64 exec, 1
	global_atomic_add v2, v3, s[4:5]
	s_mov_b64 exec, -1
	s_branch .LBB0_781
.Lpf_nouprel:
	s_cmp_eq_u32 s2, 5
	s_cbranch_scc1 .LBB0_781
	s_cmp_eq_u32 s2, 14
	s_cbranch_scc1 .LBB0_781
	s_cmp_eq_u32 s2, 9
	s_cbranch_scc1 .LBB0_781
	s_cmp_eq_u32 s2, 18
	s_cbranch_scc1 .LBB0_781
	s_cmp_eq_u32 s2, 4
	s_cbranch_scc1 .LBB0_781
	s_cmp_eq_u32 s2, 13
	s_cbranch_scc1 .LBB0_781
	s_waitcnt vmcnt(0)
	s_waitcnt lgkmcnt(0)
	s_barrier
	s_mov_b64 s[2:3], exec
	v_readlane_b32 s4, v253, 7
	v_readlane_b32 s5, v253, 8
	s_and_b64 s[4:5], s[2:3], s[4:5]
	s_mov_b64 exec, s[4:5]
	s_cbranch_execz .LBB0_780
	s_add_i32 s13, 0, 0x24000
	s_mov_b64 s[4:5], src_shared_base
	s_cmp_lg_u32 s13, -1
	s_cselect_b32 s4, s13, 0
	s_cselect_b32 s6, s5, 0
	s_add_i32 s12, 0, 0x24004
	s_cmp_lg_u32 s12, -1
	v_mov_b32_e32 v2, s4
	v_mov_b32_e32 v3, s6
	s_cselect_b32 s4, s12, 0
	s_cselect_b32 s5, s5, 0
	s_waitcnt vmcnt(0) expcnt(0) lgkmcnt(0)
	s_and_b32 s4, s101, 0xffff
	v_mov_b32_e32 v4, s4
	v_mov_b32_e32 v2, s4
	v_mov_b32_e32 v3, s5
	s_lshr_b32 s4, s101, 16
	v_mov_b32_e32 v2, s4
	s_waitcnt vmcnt(0) lgkmcnt(0)
	v_cmp_eq_u32_e32 vcc, 0, v4
	s_and_saveexec_b64 s[4:5], vcc
	s_cbranch_execz .LBB0_744
	s_mov_b32 s14, 1
	s_branch .LBB0_732
